# v103 + barrier spin polls without s_sleep (spin-wait cadence)
# speedup vs baseline: 1.0114x; 1.0114x over previous
.LBB0_148:
	s_nop 7
	global_load_dword v2, v0, s[6:7] offset:32 sc1
	s_waitcnt vmcnt(0)
	v_and_b32_e32 v2, 0xffff0000, v2
	v_cmp_ne_u32_e32 vcc, v2, v1
	s_or_b64 s[8:9], vcc, s[8:9]
	s_andn2_b64 exec, exec, s[8:9]
	s_cbranch_execnz .LBB0_148

.LBB0_180:
	v_readlane_b32 s4, v253, 16
	v_readlane_b32 s5, v253, 17
	v_readlane_b32 s1, v254, 31
	s_mov_b64 s[8:9], -1
	s_mov_b64 s[10:11], -1
	s_nop 1
	global_load_dword v0, v1, s[4:5] sc1
	v_readlane_b32 s4, v253, 18
	v_readlane_b32 s5, v253, 19
	s_waitcnt lgkmcnt(0)
	s_nop 3
	global_load_dword v2, v1, s[4:5] sc1
	v_readlane_b32 s4, v253, 20
	v_readlane_b32 s5, v253, 21
	s_nop 4
	global_load_dword v3, v1, s[4:5] sc1
	v_readlane_b32 s4, v253, 22
	v_readlane_b32 s5, v253, 23
	s_nop 4
	global_load_dword v4, v1, s[4:5] sc1
	v_readlane_b32 s4, v253, 24
	v_readlane_b32 s5, v253, 25
	s_nop 4
	global_load_dword v5, v1, s[4:5] sc1
	v_readlane_b32 s4, v253, 26
	v_readlane_b32 s5, v253, 27
	s_nop 4
	global_load_dword v6, v1, s[4:5] sc1
	v_readlane_b32 s4, v253, 28
	v_readlane_b32 s5, v253, 29
	s_nop 4
	global_load_dword v7, v1, s[4:5] sc1
	v_readlane_b32 s4, v253, 30
	v_readlane_b32 s5, v253, 31
	s_nop 4
	global_load_dword v8, v1, s[4:5] sc1
	v_readlane_b32 s4, v253, 32
	v_readlane_b32 s5, v253, 33
	s_nop 4
	global_load_dword v9, v1, s[4:5] sc1
	v_readlane_b32 s4, v253, 34
	v_readlane_b32 s5, v253, 35
	s_nop 4
	global_load_dword v10, v1, s[4:5] sc1
	v_readlane_b32 s4, v253, 36
	v_readlane_b32 s5, v253, 37
	s_nop 4
	global_load_dword v11, v1, s[4:5] sc1
	v_readlane_b32 s4, v253, 38
	v_readlane_b32 s5, v253, 39
	s_nop 4
	global_load_dword v12, v1, s[4:5] sc1
	v_readlane_b32 s4, v253, 40
	v_readlane_b32 s5, v253, 41
	s_nop 4
	global_load_dword v13, v1, s[4:5] sc1
	v_readlane_b32 s4, v253, 42
	v_readlane_b32 s5, v253, 43
	s_nop 4
	global_load_dword v14, v1, s[4:5] sc1
	v_readlane_b32 s4, v253, 44
	v_readlane_b32 s5, v253, 45
	s_nop 4
	global_load_dword v15, v1, s[4:5] sc1
	v_readlane_b32 s4, v253, 46
	v_readlane_b32 s5, v253, 47
	s_nop 4
	global_load_dword v16, v1, s[4:5] sc1
	s_waitcnt vmcnt(0)
	v_add_u32_e32 v17, v2, v0
	v_add_u32_e32 v17, v17, v3
	v_add_u32_e32 v17, v17, v4
	v_add_u32_e32 v17, v17, v5
	v_add_u32_e32 v17, v17, v6
	v_add_u32_e32 v17, v17, v7
	v_add_u32_e32 v17, v17, v8
	v_add_u32_e32 v17, v17, v9
	v_add_u32_e32 v17, v17, v10
	v_add_u32_e32 v17, v17, v11
	v_add_u32_e32 v17, v17, v12
	v_add_u32_e32 v17, v17, v13
	v_add_u32_e32 v17, v17, v14
	v_add_u32_e32 v17, v17, v15
	v_add_u32_e32 v17, v17, v16
	v_cmp_eq_u32_e32 vcc, s1, v17
	s_cbranch_vccnz .LBB0_179
	s_and_b32 s1, s0, 0xff
	s_cmp_eq_u32 s1, 0
	s_mov_b64 s[12:13], -1
	s_nop 7
	s_cbranch_scc0 .LBB0_184
	v_readlane_b32 s4, v253, 14
	v_readlane_b32 s5, v253, 15
	s_nop 4
	global_load_dword v17, v1, s[4:5] sc1
	s_waitcnt vmcnt(0)
	v_cmp_eq_u32_e32 vcc, 0, v17
	s_cbranch_vccnz .LBB0_186
	s_mov_b64 s[12:13], 0

.LBB0_198:
	s_and_b32 s1, s0, 0xff
	s_mov_b64 s[22:23], -1
	s_cmp_lg_u32 s1, 0
	s_mov_b64 s[40:41], -1
	s_nop 7
	s_cbranch_scc1 .LBB0_201
	v_readlane_b32 s4, v253, 14
	v_readlane_b32 s5, v253, 15
	s_nop 4
	global_load_dword v2, v1, s[4:5] sc1
	s_waitcnt vmcnt(0)
	v_cmp_eq_u32_e32 vcc, 0, v2
	s_cbranch_vccnz .LBB0_203
	s_mov_b64 s[40:41], 0
	s_mov_b64 s[38:39], -1

.LBB0_299:
	v_readlane_b32 s4, v253, 16
	v_readlane_b32 s5, v253, 17
	v_readlane_b32 s1, v254, 31
	s_mov_b64 s[8:9], -1
	s_mov_b64 s[10:11], -1
	s_nop 1
	global_load_dword v0, v1, s[4:5] sc1
	v_readlane_b32 s4, v253, 18
	v_readlane_b32 s5, v253, 19
	s_waitcnt lgkmcnt(0)
	s_nop 3
	global_load_dword v2, v1, s[4:5] sc1
	v_readlane_b32 s4, v253, 20
	v_readlane_b32 s5, v253, 21
	s_waitcnt vmcnt(0)
	v_add_u32_e32 v17, v2, v0
	s_nop 2
	global_load_dword v3, v1, s[4:5] sc1
	v_readlane_b32 s4, v253, 22
	v_readlane_b32 s5, v253, 23
	s_waitcnt vmcnt(0)
	v_add_u32_e32 v17, v17, v3
	s_nop 2
	global_load_dword v4, v1, s[4:5] sc1
	v_readlane_b32 s4, v253, 24
	v_readlane_b32 s5, v253, 25
	s_waitcnt vmcnt(0)
	v_add_u32_e32 v17, v17, v4
	s_nop 2
	global_load_dword v5, v1, s[4:5] sc1
	v_readlane_b32 s4, v253, 26
	v_readlane_b32 s5, v253, 27
	s_waitcnt vmcnt(0)
	v_add_u32_e32 v17, v17, v5
	s_nop 2
	global_load_dword v6, v1, s[4:5] sc1
	v_readlane_b32 s4, v253, 28
	v_readlane_b32 s5, v253, 29
	s_waitcnt vmcnt(0)
	v_add_u32_e32 v17, v17, v6
	s_nop 2
	global_load_dword v7, v1, s[4:5] sc1
	v_readlane_b32 s4, v253, 30
	v_readlane_b32 s5, v253, 31
	s_waitcnt vmcnt(0)
	v_add_u32_e32 v17, v17, v7
	s_nop 2
	global_load_dword v8, v1, s[4:5] sc1
	v_readlane_b32 s4, v253, 32
	v_readlane_b32 s5, v253, 33
	s_waitcnt vmcnt(0)
	v_add_u32_e32 v17, v17, v8
	s_nop 2
	global_load_dword v9, v1, s[4:5] sc1
	v_readlane_b32 s4, v253, 34
	v_readlane_b32 s5, v253, 35
	s_waitcnt vmcnt(0)
	v_add_u32_e32 v17, v17, v9
	s_nop 2
	global_load_dword v10, v1, s[4:5] sc1
	v_readlane_b32 s4, v253, 36
	v_readlane_b32 s5, v253, 37
	s_waitcnt vmcnt(0)
	v_add_u32_e32 v17, v17, v10
	s_nop 2
	global_load_dword v11, v1, s[4:5] sc1
	v_readlane_b32 s4, v253, 38
	v_readlane_b32 s5, v253, 39
	s_waitcnt vmcnt(0)
	v_add_u32_e32 v17, v17, v11
	s_nop 2
	global_load_dword v12, v1, s[4:5] sc1
	v_readlane_b32 s4, v253, 40
	v_readlane_b32 s5, v253, 41
	s_waitcnt vmcnt(0)
	v_add_u32_e32 v17, v17, v12
	s_nop 2
	global_load_dword v13, v1, s[4:5] sc1
	v_readlane_b32 s4, v253, 42
	v_readlane_b32 s5, v253, 43
	s_waitcnt vmcnt(0)
	v_add_u32_e32 v17, v17, v13
	s_nop 2
	global_load_dword v14, v1, s[4:5] sc1
	v_readlane_b32 s4, v253, 44
	v_readlane_b32 s5, v253, 45
	s_waitcnt vmcnt(0)
	v_add_u32_e32 v17, v17, v14
	s_nop 2
	global_load_dword v15, v1, s[4:5] sc1
	v_readlane_b32 s4, v253, 46
	v_readlane_b32 s5, v253, 47
	s_waitcnt vmcnt(0)
	v_add_u32_e32 v17, v17, v15
	s_nop 2
	global_load_dword v16, v1, s[4:5] sc1
	s_waitcnt vmcnt(0)
	v_add_u32_e32 v17, v17, v16
	v_cmp_eq_u32_e32 vcc, s1, v17
	s_cbranch_vccnz .LBB0_298
	s_and_b32 s1, s0, 0xff
	s_cmp_eq_u32 s1, 0
	s_mov_b64 s[12:13], -1
	s_nop 7
	s_cbranch_scc0 .LBB0_303
	v_readlane_b32 s4, v253, 14
	v_readlane_b32 s5, v253, 15
	s_nop 4
	global_load_dword v17, v1, s[4:5] sc1
	s_waitcnt vmcnt(0)
	v_cmp_eq_u32_e32 vcc, 0, v17
	s_cbranch_vccnz .LBB0_305
	s_mov_b64 s[12:13], 0

.LBB0_663:
	v_readlane_b32 s4, v253, 16
	v_readlane_b32 s5, v253, 17
	v_readlane_b32 s2, v254, 31
	s_mov_b64 s[10:11], -1
	s_mov_b64 s[12:13], -1
	s_nop 1
	global_load_dword v0, v1, s[4:5] sc1
	v_readlane_b32 s4, v253, 18
	v_readlane_b32 s5, v253, 19
	s_waitcnt lgkmcnt(0)
	s_nop 3
	global_load_dword v2, v1, s[4:5] sc1
	v_readlane_b32 s4, v253, 20
	v_readlane_b32 s5, v253, 21
	s_waitcnt vmcnt(0)
	v_add_u32_e32 v17, v2, v0
	s_nop 2
	global_load_dword v3, v1, s[4:5] sc1
	v_readlane_b32 s4, v253, 22
	v_readlane_b32 s5, v253, 23
	s_waitcnt vmcnt(0)
	v_add_u32_e32 v17, v17, v3
	s_nop 2
	global_load_dword v4, v1, s[4:5] sc1
	v_readlane_b32 s4, v253, 24
	v_readlane_b32 s5, v253, 25
	s_waitcnt vmcnt(0)
	v_add_u32_e32 v17, v17, v4
	s_nop 2
	global_load_dword v5, v1, s[4:5] sc1
	v_readlane_b32 s4, v253, 26
	v_readlane_b32 s5, v253, 27
	s_waitcnt vmcnt(0)
	v_add_u32_e32 v17, v17, v5
	s_nop 2
	global_load_dword v6, v1, s[4:5] sc1
	v_readlane_b32 s4, v253, 28
	v_readlane_b32 s5, v253, 29
	s_waitcnt vmcnt(0)
	v_add_u32_e32 v17, v17, v6
	s_nop 2
	global_load_dword v7, v1, s[4:5] sc1
	v_readlane_b32 s4, v253, 30
	v_readlane_b32 s5, v253, 31
	s_waitcnt vmcnt(0)
	v_add_u32_e32 v17, v17, v7
	s_nop 2
	global_load_dword v8, v1, s[4:5] sc1
	v_readlane_b32 s4, v253, 32
	v_readlane_b32 s5, v253, 33
	s_waitcnt vmcnt(0)
	v_add_u32_e32 v17, v17, v8
	s_nop 2
	global_load_dword v9, v1, s[4:5] sc1
	v_readlane_b32 s4, v253, 34
	v_readlane_b32 s5, v253, 35
	s_waitcnt vmcnt(0)
	v_add_u32_e32 v17, v17, v9
	s_nop 2
	global_load_dword v10, v1, s[4:5] sc1
	v_readlane_b32 s4, v253, 36
	v_readlane_b32 s5, v253, 37
	s_waitcnt vmcnt(0)
	v_add_u32_e32 v17, v17, v10
	s_nop 2
	global_load_dword v11, v1, s[4:5] sc1
	v_readlane_b32 s4, v253, 38
	v_readlane_b32 s5, v253, 39
	s_waitcnt vmcnt(0)
	v_add_u32_e32 v17, v17, v11
	s_nop 2
	global_load_dword v12, v1, s[4:5] sc1
	v_readlane_b32 s4, v253, 40
	v_readlane_b32 s5, v253, 41
	s_waitcnt vmcnt(0)
	v_add_u32_e32 v17, v17, v12
	s_nop 2
	global_load_dword v13, v1, s[4:5] sc1
	v_readlane_b32 s4, v253, 42
	v_readlane_b32 s5, v253, 43
	s_waitcnt vmcnt(0)
	v_add_u32_e32 v17, v17, v13
	s_nop 2
	global_load_dword v14, v1, s[4:5] sc1
	v_readlane_b32 s4, v253, 44
	v_readlane_b32 s5, v253, 45
	s_waitcnt vmcnt(0)
	v_add_u32_e32 v17, v17, v14
	s_nop 2
	global_load_dword v15, v1, s[4:5] sc1
	v_readlane_b32 s4, v253, 46
	v_readlane_b32 s5, v253, 47
	s_waitcnt vmcnt(0)
	v_add_u32_e32 v17, v17, v15
	s_nop 2
	global_load_dword v16, v1, s[4:5] sc1
	s_waitcnt vmcnt(0)
	v_add_u32_e32 v17, v17, v16
	v_cmp_eq_u32_e32 vcc, s2, v17
	s_cbranch_vccnz .LBB0_662
	s_and_b32 s2, s1, 0xff
	s_cmp_eq_u32 s2, 0
	s_mov_b64 s[20:21], -1
	s_nop 7
	s_cbranch_scc0 .LBB0_667
	v_readlane_b32 s4, v253, 14
	v_readlane_b32 s5, v253, 15
	s_nop 4
	global_load_dword v17, v1, s[4:5] sc1
	s_waitcnt vmcnt(0)
	v_cmp_eq_u32_e32 vcc, 0, v17
	s_cbranch_vccnz .LBB0_669
	s_mov_b64 s[20:21], 0

.LBB0_681:
	s_and_b32 s2, s1, 0xff
	s_mov_b64 s[38:39], -1
	s_cmp_lg_u32 s2, 0
	s_mov_b64 s[42:43], -1
	s_nop 7
	s_cbranch_scc1 .LBB0_684
	v_readlane_b32 s4, v253, 14
	v_readlane_b32 s5, v253, 15
	s_nop 4
	global_load_dword v2, v1, s[4:5] sc1
	s_waitcnt vmcnt(0)
	v_cmp_eq_u32_e32 vcc, 0, v2
	s_cbranch_vccnz .LBB0_686
	s_mov_b64 s[42:43], 0
	s_mov_b64 s[40:41], -1
